# grid barrier for syncs 2..8: arrivals counted in eight per-XCC shard words (64 B apart) instead of one word, all eight polled by lanes 0-7 of one load
# speedup vs baseline: 1.0093x; 1.0093x over previous
; DI void phase0(const Params& p, char* lds0) {
;     ...
;   if (bid == 0 && threadIdx.x < 128) ((int*)(ws + WS_CNT))[threadIdx.x] = 0;
.LBB0_15:
	s_load_dwordx2 s[12:13], s[74:75], 0xe0
	s_cmp_eq_u32 s2, 0
	s_movk_i32 s3, 0x100
	s_cselect_b64 s[4:5], -1, 0
	v_cmp_gt_u32_e32 vcc, s3, v2
	s_and_b64 s[6:7], s[4:5], vcc
	s_and_saveexec_b64 s[4:5], s[6:7]
	s_cbranch_execz .LBB0_17
	v_mov_b32_e32 v3, 0
	s_waitcnt lgkmcnt(0)
	v_lshl_add_u64 v[4:5], v[2:3], 2, s[12:13]
	v_add_co_u32_e32 v4, vcc, 0x194000, v4
	s_nop 1
	v_addc_co_u32_e32 v5, vcc, 0, v5, vcc
	global_store_dword v[4:5], v3, off

; #define RUN(k, call) if (lo <= (k) && (k) < hi) { if ((k) > lo) grid.sync(); if (PHMASK & (1 << (k))) { call; } }
; __global__ void __launch_bounds__(NT, 2) fwd_kernel(Params p) {
;     ...
;   RUN(2, phase2(p, lds))
.LBB0_82:
	s_cmp_lt_i32 s78, 3
	s_cselect_b64 s[4:5], -1, 0
	s_cmp_gt_i32 s79, 2
	s_cselect_b64 s[0:1], -1, 0
	s_and_b64 s[0:1], s[4:5], s[0:1]
	s_andn2_b64 vcc, exec, s[0:1]
	s_cbranch_vccnz .LBB0_137
	s_andn2_b64 vcc, exec, s[6:7]
	s_cbranch_vccnz .LBB0_95
	v_and_b32_e32 v1, 0x3fffffff, v0
	v_cmp_eq_u32_e32 vcc, 0, v1
	s_waitcnt lgkmcnt(0)
	s_barrier
	s_and_saveexec_b64 s[0:1], vcc
	s_cbranch_execz .LBB0_94
	buffer_wbl2 sc1
	s_load_dwordx2 s[6:7], s[74:75], 0xe0
	v_mov_b32_e32 v3, 1
	s_getreg_b32 vcc_lo, hwreg(HW_REG_XCC_ID)
	s_and_b32 vcc_lo, vcc_lo, 7
	s_lshl_b32 vcc_lo, vcc_lo, 6
	v_mov_b32_e32 v1, vcc_lo
	s_waitcnt vmcnt(0) lgkmcnt(0)
	s_add_u32 s6, s6, 0x194200
	s_addc_u32 s7, s7, 0
	global_atomic_add v1, v3, s[6:7]
	s_mov_b64 exec, 0xff
	v_mbcnt_lo_u32_b32 v1, -1, 0
	v_lshlrev_b32_e32 v1, 6, v1
.Lgb2_spin:
	global_load_dword v3, v1, s[6:7] sc1
	s_waitcnt vmcnt(0)
	v_cmp_gt_u32_e32 vcc, 32, v3
	s_cbranch_vccz .Lgb2_out
	s_sleep 1
	s_branch .Lgb2_spin

; #define RUN(k, call) if (lo <= (k) && (k) < hi) { if ((k) > lo) grid.sync(); if (PHMASK & (1 << (k))) { call; } }
; __global__ void __launch_bounds__(NT, 2) fwd_kernel(Params p) {
;     ...
;   RUN(3, phase3(p, lds))
.LBB0_137:
	s_cmp_lt_i32 s78, 4
	s_cselect_b64 s[16:17], -1, 0
	s_cmp_gt_i32 s79, 3
	s_cselect_b64 s[0:1], -1, 0
	s_and_b64 s[0:1], s[16:17], s[0:1]
	s_andn2_b64 vcc, exec, s[0:1]
	s_cbranch_vccnz .LBB0_212
	s_andn2_b64 vcc, exec, s[4:5]
	s_cbranch_vccnz .LBB0_150
	v_and_b32_e32 v1, 0x3fffffff, v0
	v_cmp_eq_u32_e32 vcc, 0, v1
	s_waitcnt lgkmcnt(0)
	s_barrier
	s_and_saveexec_b64 s[0:1], vcc
	s_cbranch_execz .LBB0_149
	buffer_wbl2 sc1
	s_load_dwordx2 s[4:5], s[74:75], 0xe0
	v_mov_b32_e32 v3, 1
	s_getreg_b32 vcc_lo, hwreg(HW_REG_XCC_ID)
	s_and_b32 vcc_lo, vcc_lo, 7
	s_lshl_b32 vcc_lo, vcc_lo, 6
	v_mov_b32_e32 v1, vcc_lo
	s_waitcnt vmcnt(0) lgkmcnt(0)
	s_add_u32 s4, s4, 0x194200
	s_addc_u32 s5, s5, 0
	global_atomic_add v1, v3, s[4:5]
	s_mov_b64 exec, 0xff
	v_mbcnt_lo_u32_b32 v1, -1, 0
	v_lshlrev_b32_e32 v1, 6, v1
.Lgb3_spin:
	global_load_dword v3, v1, s[4:5] sc1
	s_waitcnt vmcnt(0)
	v_cmp_gt_u32_e32 vcc, 64, v3
	s_cbranch_vccz .Lgb3_out
	s_sleep 1
	s_branch .Lgb3_spin

; #define RUN(k, call) if (lo <= (k) && (k) < hi) { if ((k) > lo) grid.sync(); if (PHMASK & (1 << (k))) { call; } }
; __global__ void __launch_bounds__(NT, 2) fwd_kernel(Params p) {
;     ...
;   RUN(4, phase4(p, lds))
.LBB0_212:
	s_cmp_gt_i32 s78, 4
	s_cselect_b64 s[0:1], -1, 0
	s_cmp_lt_i32 s78, 5
	s_cselect_b64 s[4:5], -1, 0
	s_cmp_gt_i32 s79, 4
	s_cselect_b64 s[6:7], -1, 0
	s_and_b64 s[4:5], s[4:5], s[6:7]
	s_andn2_b64 vcc, exec, s[4:5]
	s_cbranch_vccnz .LBB0_232
	s_andn2_b64 vcc, exec, s[16:17]
	s_cbranch_vccnz .LBB0_225
	v_and_b32_e32 v1, 0x3fffffff, v0
	v_cmp_eq_u32_e32 vcc, 0, v1
	s_waitcnt lgkmcnt(0)
	s_barrier
	s_and_saveexec_b64 s[4:5], vcc
	s_cbranch_execz .LBB0_224
	buffer_wbl2 sc1
	s_load_dwordx2 s[6:7], s[74:75], 0xe0
	v_mov_b32_e32 v3, 1
	s_getreg_b32 vcc_lo, hwreg(HW_REG_XCC_ID)
	s_and_b32 vcc_lo, vcc_lo, 7
	s_lshl_b32 vcc_lo, vcc_lo, 6
	v_mov_b32_e32 v1, vcc_lo
	s_waitcnt vmcnt(0) lgkmcnt(0)
	s_add_u32 s6, s6, 0x194200
	s_addc_u32 s7, s7, 0
	global_atomic_add v1, v3, s[6:7]
	s_mov_b64 exec, 0xff
	v_mbcnt_lo_u32_b32 v1, -1, 0
	v_lshlrev_b32_e32 v1, 6, v1
.Lgb4_spin:
	global_load_dword v3, v1, s[6:7] sc1
	s_waitcnt vmcnt(0)
	v_cmp_gt_u32_e32 vcc, 96, v3
	s_cbranch_vccz .Lgb4_out
	s_sleep 1
	s_branch .Lgb4_spin

; #define RUN(k, call) if (lo <= (k) && (k) < hi) { if ((k) > lo) grid.sync(); if (PHMASK & (1 << (k))) { call; } }
; __global__ void __launch_bounds__(NT, 2) fwd_kernel(Params p) {
;     ...
;   RUN(5, phase5(p, lds))
.LBB0_235:
.LBB0_236:
	v_and_b32_e32 v1, 0x3fffffff, v0
	v_cmp_eq_u32_e32 vcc, 0, v1
	s_waitcnt lgkmcnt(0)
	s_barrier
	s_and_saveexec_b64 s[0:1], vcc
	s_cbranch_execz .LBB0_246
	buffer_wbl2 sc1
	s_load_dwordx2 s[4:5], s[74:75], 0xe0
	v_mov_b32_e32 v3, 1
	s_getreg_b32 vcc_lo, hwreg(HW_REG_XCC_ID)
	s_and_b32 vcc_lo, vcc_lo, 7
	s_lshl_b32 vcc_lo, vcc_lo, 6
	v_mov_b32_e32 v1, vcc_lo
	s_waitcnt vmcnt(0) lgkmcnt(0)
	s_add_u32 s4, s4, 0x194200
	s_addc_u32 s5, s5, 0
	global_atomic_add v1, v3, s[4:5]
	s_mov_b64 exec, 0xff
	v_mbcnt_lo_u32_b32 v1, -1, 0
	v_lshlrev_b32_e32 v1, 6, v1
.Lgb5_spin:
	global_load_dword v3, v1, s[4:5] sc1
	s_waitcnt vmcnt(0)
	v_cmp_gt_u32_e32 vcc, 128, v3
	s_cbranch_vccz .Lgb5_out
	s_sleep 1
	s_branch .Lgb5_spin

; #define RUN(k, call) if (lo <= (k) && (k) < hi) { if ((k) > lo) grid.sync(); if (PHMASK & (1 << (k))) { call; } }
; __global__ void __launch_bounds__(NT, 2) fwd_kernel(Params p) {
;     ...
;   RUN(6, phase_moe(p, lds, 0))
.Lgb6_spin:
	global_load_dword v3, v1, s[4:5] sc1
	s_waitcnt vmcnt(0)
	v_cmp_gt_u32_e32 vcc, 160, v3
	s_cbranch_vccz .Lgb6_out
	s_sleep 1
	s_branch .Lgb6_spin

; #define RUN(k, call) if (lo <= (k) && (k) < hi) { if ((k) > lo) grid.sync(); if (PHMASK & (1 << (k))) { call; } }
; __global__ void __launch_bounds__(NT, 2) fwd_kernel(Params p) {
;     ...
;   RUN(7, phase_moe(p, lds, 1))
.LBB0_305:
.LBB0_306:
	v_and_b32_e32 v1, 0x3fffffff, v0
	v_cmp_eq_u32_e32 vcc, 0, v1
	s_barrier
	s_and_saveexec_b64 s[0:1], vcc
	s_cbranch_execz .LBB0_316
	buffer_wbl2 sc1
	s_load_dwordx2 s[4:5], s[74:75], 0xe0
	v_mov_b32_e32 v3, 1
	s_getreg_b32 vcc_lo, hwreg(HW_REG_XCC_ID)
	s_and_b32 vcc_lo, vcc_lo, 7
	s_lshl_b32 vcc_lo, vcc_lo, 6
	v_mov_b32_e32 v1, vcc_lo
	s_waitcnt vmcnt(0) lgkmcnt(0)
	s_add_u32 s4, s4, 0x194200
	s_addc_u32 s5, s5, 0
	global_atomic_add v1, v3, s[4:5]
	s_mov_b64 exec, 0xff
	v_mbcnt_lo_u32_b32 v1, -1, 0
	v_lshlrev_b32_e32 v1, 6, v1
.Lgb7_spin:
	global_load_dword v3, v1, s[4:5] sc1
	s_waitcnt vmcnt(0)
	v_cmp_gt_u32_e32 vcc, 192, v3
	s_cbranch_vccz .Lgb7_out
	s_sleep 1
	s_branch .Lgb7_spin

; #define RUN(k, call) if (lo <= (k) && (k) < hi) { if ((k) > lo) grid.sync(); if (PHMASK & (1 << (k))) { call; } }
; __global__ void __launch_bounds__(NT, 2) fwd_kernel(Params p) {
;     ...
;   RUN(8, phase_moe(p, lds, 2))
.Lgb8_spin:
	global_load_dword v3, v1, s[4:5] sc1
	s_waitcnt vmcnt(0)
	v_cmp_gt_u32_e32 vcc, 224, v3
	s_cbranch_vccz .Lgb8_out
	s_sleep 1
	s_branch .Lgb8_spin
